# final top-256 selection: one bin of head-room below the lowest key so that no list entry lands in the uncounted bin 0
# baseline (speedup 1.0000x reference)
.LBB0_223:
	v_or_b32_e32 v9, s54, v143
	v_lshl_add_u32 v23, v9, 2, 0
	v_add_u32_e32 v15, 0x24000, v23
	ds_read_b32 v8, v15
	s_movk_i32 s2, 0x100
	s_waitcnt lgkmcnt(0)
	v_cmp_lt_i32_e32 vcc, s2, v8
	s_and_saveexec_b64 s[2:3], vcc
	s_cbranch_execz .LBB0_222
	v_readfirstlane_b32 s8, v9
	v_readfirstlane_b32 s24, v143
	s_mul_i32 s9, s8, 0xc00
	s_mul_i32 s10, s8, 0x600
	s_add_i32 s10, s10, 0x18000
	s_lshl_b32 s11, s8, 2
	s_add_i32 s11, s11, 0x24000
	v_mov_b32_e32 v40, s11
	ds_read_b32 v92, v40
	s_waitcnt lgkmcnt(0)
	v_readfirstlane_b32 s12, v92
	s_add_i32 s13, s12, -1
	v_min_u32_e32 v93, s13, v190
	v_lshl_add_u32 v94, v93, 2, s9
	v_lshl_add_u32 v93, v93, 1, s10
	ds_read_b32 v161, v94
	ds_read_u16 v142, v93
	v_min_u32_e32 v95, s13, v185
	v_lshl_add_u32 v120, v95, 2, s9
	v_lshl_add_u32 v95, v95, 1, s10
	ds_read_b32 v162, v120
	ds_read_u16 v143, v95
	v_min_u32_e32 v93, s13, v192
	v_lshl_add_u32 v94, v93, 2, s9
	v_lshl_add_u32 v93, v93, 1, s10
	ds_read_b32 v163, v94
	ds_read_u16 v144, v93
	v_min_u32_e32 v95, s13, v191
	v_lshl_add_u32 v120, v95, 2, s9
	v_lshl_add_u32 v95, v95, 1, s10
	ds_read_b32 v164, v120
	ds_read_u16 v145, v95
	v_min_u32_e32 v93, s13, v0
	v_lshl_add_u32 v94, v93, 2, s9
	v_lshl_add_u32 v93, v93, 1, s10
	ds_read_b32 v165, v94
	ds_read_u16 v146, v93
	v_min_u32_e32 v95, s13, v1
	v_lshl_add_u32 v120, v95, 2, s9
	v_lshl_add_u32 v95, v95, 1, s10
	ds_read_b32 v166, v120
	ds_read_u16 v148, v95
	v_min_u32_e32 v93, s13, v2
	v_lshl_add_u32 v94, v93, 2, s9
	v_lshl_add_u32 v93, v93, 1, s10
	ds_read_b32 v167, v94
	ds_read_u16 v149, v93
	v_min_u32_e32 v95, s13, v3
	v_lshl_add_u32 v120, v95, 2, s9
	v_lshl_add_u32 v95, v95, 1, s10
	ds_read_b32 v168, v120
	ds_read_u16 v150, v95
	v_min_u32_e32 v93, s13, v6
	v_lshl_add_u32 v94, v93, 2, s9
	v_lshl_add_u32 v93, v93, 1, s10
	ds_read_b32 v169, v94
	ds_read_u16 v152, v93
	v_min_u32_e32 v95, s13, v7
	v_lshl_add_u32 v120, v95, 2, s9
	v_lshl_add_u32 v95, v95, 1, s10
	ds_read_b32 v170, v120
	ds_read_u16 v153, v95
	v_min_u32_e32 v93, s13, v4
	v_lshl_add_u32 v94, v93, 2, s9
	v_lshl_add_u32 v93, v93, 1, s10
	ds_read_b32 v171, v94
	ds_read_u16 v159, v93
	v_min_u32_e32 v95, s13, v5
	v_lshl_add_u32 v120, v95, 2, s9
	v_lshl_add_u32 v95, v95, 1, s10
	ds_read_b32 v172, v120
	ds_read_u16 v160, v95
	ds_write_b128 v127, a[206:209]
	s_waitcnt lgkmcnt(1)
	v_ashrrev_i32_e32 v93, 31, v161
	v_or_b32_e32 v93, 0x80000000, v93
	v_xor_b32_e32 v108, v161, v93
	v_ashrrev_i32_e32 v94, 31, v162
	v_or_b32_e32 v94, 0x80000000, v94
	v_xor_b32_e32 v109, v162, v94
	v_ashrrev_i32_e32 v93, 31, v163
	v_or_b32_e32 v93, 0x80000000, v93
	v_xor_b32_e32 v110, v163, v93
	v_ashrrev_i32_e32 v94, 31, v164
	v_or_b32_e32 v94, 0x80000000, v94
	v_xor_b32_e32 v111, v164, v94
	v_ashrrev_i32_e32 v93, 31, v165
	v_or_b32_e32 v93, 0x80000000, v93
	v_xor_b32_e32 v112, v165, v93
	v_ashrrev_i32_e32 v94, 31, v166
	v_or_b32_e32 v94, 0x80000000, v94
	v_xor_b32_e32 v113, v166, v94
	v_ashrrev_i32_e32 v93, 31, v167
	v_or_b32_e32 v93, 0x80000000, v93
	v_xor_b32_e32 v114, v167, v93
	v_ashrrev_i32_e32 v94, 31, v168
	v_or_b32_e32 v94, 0x80000000, v94
	v_xor_b32_e32 v115, v168, v94
	v_ashrrev_i32_e32 v93, 31, v169
	v_or_b32_e32 v93, 0x80000000, v93
	v_xor_b32_e32 v116, v169, v93
	v_ashrrev_i32_e32 v94, 31, v170
	v_or_b32_e32 v94, 0x80000000, v94
	v_xor_b32_e32 v117, v170, v94
	v_ashrrev_i32_e32 v93, 31, v171
	v_or_b32_e32 v93, 0x80000000, v93
	v_xor_b32_e32 v118, v171, v93
	v_ashrrev_i32_e32 v94, 31, v172
	v_or_b32_e32 v94, 0x80000000, v94
	v_xor_b32_e32 v119, v172, v94
	v_max3_u32 v92, v108, v109, v110
	v_min3_u32 v93, v108, v109, v110
	v_max3_u32 v92, v111, v112, v92
	v_min3_u32 v93, v111, v112, v93
	v_max3_u32 v92, v113, v114, v92
	v_min3_u32 v93, v113, v114, v93
	v_max3_u32 v92, v115, v116, v92
	v_min3_u32 v93, v115, v116, v93
	v_max3_u32 v92, v117, v118, v92
	v_min3_u32 v93, v117, v118, v93
	v_max_u32_e32 v92, v119, v92
	v_min_u32_e32 v93, v119, v93
	s_nop 0
	v_max_u32_dpp v92, v92, v92 quad_perm:[1,0,3,2] row_mask:0xf bank_mask:0xf bound_ctrl:1
	v_min_u32_dpp v93, v93, v93 quad_perm:[1,0,3,2] row_mask:0xf bank_mask:0xf bound_ctrl:1
	s_nop 0
	v_max_u32_dpp v92, v92, v92 quad_perm:[2,3,0,1] row_mask:0xf bank_mask:0xf bound_ctrl:1
	v_min_u32_dpp v93, v93, v93 quad_perm:[2,3,0,1] row_mask:0xf bank_mask:0xf bound_ctrl:1
	s_nop 0
	v_max_u32_dpp v92, v92, v92 row_half_mirror row_mask:0xf bank_mask:0xf bound_ctrl:1
	v_min_u32_dpp v93, v93, v93 row_half_mirror row_mask:0xf bank_mask:0xf bound_ctrl:1
	s_nop 0
	v_max_u32_dpp v92, v92, v92 row_mirror row_mask:0xf bank_mask:0xf bound_ctrl:1
	v_min_u32_dpp v93, v93, v93 row_mirror row_mask:0xf bank_mask:0xf bound_ctrl:1
	s_nop 1
	v_readlane_b32 s15, v92, 0
	v_readlane_b32 s16, v92, 16
	v_readlane_b32 s17, v92, 32
	v_readlane_b32 s18, v92, 48
	s_max_u32 s15, s15, s16
	s_max_u32 s17, s17, s18
	s_max_u32 s15, s15, s17
	v_readlane_b32 s16, v93, 0
	v_readlane_b32 s17, v93, 16
	v_readlane_b32 s18, v93, 32
	v_readlane_b32 s19, v93, 48
	s_min_u32 s16, s16, s17
	s_min_u32 s18, s18, s19
	s_min_u32 s16, s16, s18
	s_sub_u32 s17, s15, 0x3000000
	s_cselect_b32 s17, 0, s17
	s_max_u32 s14, s16, s17
	s_sub_u32 s16, s15, s14
	s_lshr_b32 s16, s16, 7
	s_add_u32 s16, s16, 1
	s_sub_u32 s14, s14, s16
	s_cselect_b32 s14, 0, s14
	s_sub_u32 s16, s15, s14
	s_add_u32 s16, s16, 1
	s_cmpk_le_u32 s16, 0x100
	s_cbranch_scc1 .Lfn_orig
	v_mov_b32_e32 v92, s16
	v_cvt_f32_u32_e32 v92, v92
	v_rcp_f32_e32 v92, v92
	s_nop 0
	v_mul_f32_e32 v92, 0x53800000, v92
	v_cvt_u32_f32_e32 v92, v92
	s_nop 0
	v_readfirstlane_b32 s21, v92
	s_nop 1
	v_max_u32_e32 v93, s14, v108
	v_subrev_u32_e32 v93, s14, v93
	v_mul_hi_u32 v93, v93, s21
	v_min_u32_e32 v173, 0xff, v93
	v_max_u32_e32 v94, s14, v109
	v_subrev_u32_e32 v94, s14, v94
	v_mul_hi_u32 v94, v94, s21
	v_min_u32_e32 v174, 0xff, v94
	v_max_u32_e32 v95, s14, v110
	v_subrev_u32_e32 v95, s14, v95
	v_mul_hi_u32 v95, v95, s21
	v_min_u32_e32 v175, 0xff, v95
	v_max_u32_e32 v93, s14, v111
	v_subrev_u32_e32 v93, s14, v93
	v_mul_hi_u32 v93, v93, s21
	v_min_u32_e32 v176, 0xff, v93
	v_max_u32_e32 v94, s14, v112
	v_subrev_u32_e32 v94, s14, v94
	v_mul_hi_u32 v94, v94, s21
	v_min_u32_e32 v177, 0xff, v94
	v_max_u32_e32 v95, s14, v113
	v_subrev_u32_e32 v95, s14, v95
	v_mul_hi_u32 v95, v95, s21
	v_min_u32_e32 v178, 0xff, v95
	v_max_u32_e32 v93, s14, v114
	v_subrev_u32_e32 v93, s14, v93
	v_mul_hi_u32 v93, v93, s21
	v_min_u32_e32 v179, 0xff, v93
	v_max_u32_e32 v94, s14, v115
	v_subrev_u32_e32 v94, s14, v94
	v_mul_hi_u32 v94, v94, s21
	v_min_u32_e32 v180, 0xff, v94
	v_max_u32_e32 v95, s14, v116
	v_subrev_u32_e32 v95, s14, v95
	v_mul_hi_u32 v95, v95, s21
	v_min_u32_e32 v181, 0xff, v95
	v_max_u32_e32 v93, s14, v117
	v_subrev_u32_e32 v93, s14, v93
	v_mul_hi_u32 v93, v93, s21
	v_min_u32_e32 v182, 0xff, v93
	v_max_u32_e32 v94, s14, v118
	v_subrev_u32_e32 v94, s14, v94
	v_mul_hi_u32 v94, v94, s21
	v_min_u32_e32 v183, 0xff, v94
	v_max_u32_e32 v95, s14, v119
	v_subrev_u32_e32 v95, s14, v95
	v_mul_hi_u32 v95, v95, s21
	v_min_u32_e32 v184, 0xff, v95
	v_cmp_gt_u32_e64 s[26:27], s12, v190
	v_cmp_gt_u32_e64 s[28:29], s12, v185
	v_cmp_gt_u32_e64 s[30:31], s12, v192
	v_cndmask_b32_e64 v173, 0, v173, s[26:27]
	v_cmp_gt_u32_e64 s[26:27], s12, v191
	v_cndmask_b32_e64 v174, 0, v174, s[28:29]
	v_cmp_gt_u32_e64 s[28:29], s12, v0
	v_cndmask_b32_e64 v175, 0, v175, s[30:31]
	v_cmp_gt_u32_e64 s[30:31], s12, v1
	v_cndmask_b32_e64 v176, 0, v176, s[26:27]
	v_cmp_gt_u32_e64 s[26:27], s12, v2
	v_cndmask_b32_e64 v177, 0, v177, s[28:29]
	v_cmp_gt_u32_e64 s[28:29], s12, v3
	v_cndmask_b32_e64 v178, 0, v178, s[30:31]
	v_cmp_gt_u32_e64 s[30:31], s12, v6
	v_cndmask_b32_e64 v179, 0, v179, s[26:27]
	v_cmp_gt_u32_e64 s[26:27], s12, v7
	v_cndmask_b32_e64 v180, 0, v180, s[28:29]
	v_cmp_gt_u32_e64 s[28:29], s12, v4
	v_cndmask_b32_e64 v181, 0, v181, s[30:31]
	v_cmp_gt_u32_e64 s[30:31], s12, v5
	v_cndmask_b32_e64 v182, 0, v182, s[26:27]
	s_nop 0
	v_cndmask_b32_e64 v183, 0, v183, s[28:29]
	v_cndmask_b32_e64 v184, 0, v184, s[30:31]
	s_mov_b64 s[22:23], exec
	v_cmp_ne_u32_e64 s[26:27], 0, v173
	v_lshl_add_u32 v93, v173, 2, v121
	s_mov_b64 exec, s[26:27]
	ds_add_u32 v93, v252
	s_mov_b64 exec, s[22:23]
	v_cmp_ne_u32_e64 s[28:29], 0, v174
	v_lshl_add_u32 v94, v174, 2, v121
	s_mov_b64 exec, s[28:29]
	ds_add_u32 v94, v252
	s_mov_b64 exec, s[22:23]
	v_cmp_ne_u32_e64 s[30:31], 0, v175
	v_lshl_add_u32 v95, v175, 2, v121
	s_mov_b64 exec, s[30:31]
	ds_add_u32 v95, v252
	s_mov_b64 exec, s[22:23]
	v_cmp_ne_u32_e64 s[26:27], 0, v176
	v_lshl_add_u32 v93, v176, 2, v121
	s_mov_b64 exec, s[26:27]
	ds_add_u32 v93, v252
	s_mov_b64 exec, s[22:23]
	v_cmp_ne_u32_e64 s[28:29], 0, v177
	v_lshl_add_u32 v94, v177, 2, v121
	s_mov_b64 exec, s[28:29]
	ds_add_u32 v94, v252
	s_mov_b64 exec, s[22:23]
	v_cmp_ne_u32_e64 s[30:31], 0, v178
	v_lshl_add_u32 v95, v178, 2, v121
	s_mov_b64 exec, s[30:31]
	ds_add_u32 v95, v252
	s_mov_b64 exec, s[22:23]
	v_cmp_ne_u32_e64 s[26:27], 0, v179
	v_lshl_add_u32 v93, v179, 2, v121
	s_mov_b64 exec, s[26:27]
	ds_add_u32 v93, v252
	s_mov_b64 exec, s[22:23]
	v_cmp_ne_u32_e64 s[28:29], 0, v180
	v_lshl_add_u32 v94, v180, 2, v121
	s_mov_b64 exec, s[28:29]
	ds_add_u32 v94, v252
	s_mov_b64 exec, s[22:23]
	v_cmp_ne_u32_e64 s[30:31], 0, v181
	v_lshl_add_u32 v95, v181, 2, v121
	s_mov_b64 exec, s[30:31]
	ds_add_u32 v95, v252
	s_mov_b64 exec, s[22:23]
	v_cmp_ne_u32_e64 s[26:27], 0, v182
	v_lshl_add_u32 v93, v182, 2, v121
	s_mov_b64 exec, s[26:27]
	ds_add_u32 v93, v252
	s_mov_b64 exec, s[22:23]
	v_cmp_ne_u32_e64 s[28:29], 0, v183
	v_lshl_add_u32 v94, v183, 2, v121
	s_mov_b64 exec, s[28:29]
	ds_add_u32 v94, v252
	s_mov_b64 exec, s[22:23]
	v_cmp_ne_u32_e64 s[30:31], 0, v184
	v_lshl_add_u32 v95, v184, 2, v121
	s_mov_b64 exec, s[30:31]
	ds_add_u32 v95, v252
	s_mov_b64 exec, s[22:23]
	ds_read_b128 v[92:95], v127
	s_waitcnt lgkmcnt(0)
	v_add_u32_e32 v120, v92, v93
	v_add3_u32 v120, v120, v94, v95
	v_mov_b32_e32 v122, v120
	s_nop 1
	v_add_u32_dpp v122, v122, v122 row_shr:1 row_mask:0xf bank_mask:0xf bound_ctrl:1
	s_nop 1
	v_add_u32_dpp v122, v122, v122 row_shr:2 row_mask:0xf bank_mask:0xf bound_ctrl:1
	s_nop 1
	v_add_u32_dpp v122, v122, v122 row_shr:4 row_mask:0xf bank_mask:0xf bound_ctrl:1
	s_nop 1
	v_add_u32_dpp v122, v122, v122 row_shr:8 row_mask:0xf bank_mask:0xf bound_ctrl:1
	s_nop 1
	v_add_u32_dpp v122, v122, v122 row_bcast:15 row_mask:0xa bank_mask:0xf
	s_nop 1
	v_add_u32_dpp v122, v122, v122 row_bcast:31 row_mask:0xc bank_mask:0xf
	s_nop 1
	v_readlane_b32 s16, v122, 63
	s_nop 1
	v_sub_u32_e32 v123, s16, v122
	v_add_u32_e32 v124, v123, v95
	v_add_u32_e32 v126, v124, v94
	v_add_u32_e32 v128, v126, v93
	v_add_u32_e32 v129, v128, v92
	s_movk_i32 s17, 0x100
	v_lshlrev_b32_e32 v130, 2, v190
	v_cmp_le_u32_e64 s[26:27], s17, v128
	v_cmp_le_u32_e64 s[28:29], s17, v126
	v_cmp_le_u32_e64 s[30:31], s17, v124
	v_mov_b32_e32 v134, v130
	v_or_b32_e32 v131, 1, v134
	v_cndmask_b32_e64 v129, v129, v128, s[26:27]
	v_cndmask_b32_e64 v130, v130, v131, s[26:27]
	v_or_b32_e32 v131, 2, v134
	v_cndmask_b32_e64 v129, v129, v126, s[28:29]
	v_cndmask_b32_e64 v130, v130, v131, s[28:29]
	v_or_b32_e32 v131, 3, v134
	v_cndmask_b32_e64 v129, v129, v124, s[30:31]
	v_cndmask_b32_e64 v130, v130, v131, s[30:31]
	v_add_u32_e32 v132, v123, v120
	v_cmp_gt_u32_e64 s[26:27], s17, v123
	v_cmp_le_u32_e64 s[28:29], s17, v132
	s_nop 0
	s_and_b64 s[26:27], s[26:27], s[28:29]
	s_cmp_eq_u64 s[26:27], 0
	s_cbranch_scc1 .Lfn_orig
	s_ff1_i32_b64 s18, s[26:27]
	s_nop 3
	v_readlane_b32 s19, v129, s18
	v_readlane_b32 s20, v130, s18
	s_cmp_eq_u32 s20, 0
	s_cbranch_scc1 .Lfn_orig
	v_mov_b32_e32 v92, s21
	v_cvt_f32_u32_e32 v92, v92
	v_rcp_f32_e32 v92, v92
	v_mov_b32_e32 v93, s20
	v_cvt_f32_u32_e32 v93, v93
	v_mul_f32_e32 v92, 0x4f800000, v92
	v_mul_f32_e32 v92, v92, v93
	v_mul_f32_e32 v92, 0x3f7ffff0, v92
	v_cvt_u32_f32_e32 v92, v92
	s_nop 0
	v_readfirstlane_b32 s16, v92
	s_add_u32 s16, s16, s14
	s_mov_b32 s13, s16
	v_mov_b32_e32 v136, 0
	v_cmp_eq_u32_e64 s[26:27], s20, v173
	v_cmp_eq_u32_e64 s[28:29], s20, v174
	v_cmp_eq_u32_e64 s[30:31], s20, v175
	v_addc_co_u32_e64 v136, vcc, 0, v136, s[26:27]
	v_cmp_eq_u32_e64 s[26:27], s20, v176
	v_addc_co_u32_e64 v136, vcc, 0, v136, s[28:29]
	v_cmp_eq_u32_e64 s[28:29], s20, v177
	v_addc_co_u32_e64 v136, vcc, 0, v136, s[30:31]
	v_cmp_eq_u32_e64 s[30:31], s20, v178
	v_addc_co_u32_e64 v136, vcc, 0, v136, s[26:27]
	v_cmp_eq_u32_e64 s[26:27], s20, v179
	v_addc_co_u32_e64 v136, vcc, 0, v136, s[28:29]
	v_cmp_eq_u32_e64 s[28:29], s20, v180
	v_addc_co_u32_e64 v136, vcc, 0, v136, s[30:31]
	v_cmp_eq_u32_e64 s[30:31], s20, v181
	v_addc_co_u32_e64 v136, vcc, 0, v136, s[26:27]
	v_cmp_eq_u32_e64 s[26:27], s20, v182
	v_addc_co_u32_e64 v136, vcc, 0, v136, s[28:29]
	v_cmp_eq_u32_e64 s[28:29], s20, v183
	v_addc_co_u32_e64 v136, vcc, 0, v136, s[30:31]
	v_cmp_eq_u32_e64 s[30:31], s20, v184
	v_addc_co_u32_e64 v136, vcc, 0, v136, s[26:27]
	s_nop 0
	v_addc_co_u32_e64 v136, vcc, 0, v136, s[28:29]
	v_addc_co_u32_e64 v136, vcc, 0, v136, s[30:31]
	s_nop 1
	v_add_u32_dpp v136, v136, v136 quad_perm:[1,0,3,2] row_mask:0xf bank_mask:0xf bound_ctrl:1
	s_nop 1
	v_add_u32_dpp v136, v136, v136 quad_perm:[2,3,0,1] row_mask:0xf bank_mask:0xf bound_ctrl:1
	s_nop 1
	v_add_u32_dpp v136, v136, v136 row_half_mirror row_mask:0xf bank_mask:0xf bound_ctrl:1
	s_nop 1
	v_add_u32_dpp v136, v136, v136 row_mirror row_mask:0xf bank_mask:0xf bound_ctrl:1
	s_nop 1
	v_readlane_b32 s14, v136, 0
	v_readlane_b32 s15, v136, 16
	v_readlane_b32 s17, v136, 32
	v_readlane_b32 s18, v136, 48
	s_add_i32 s14, s14, s15
	s_add_i32 s17, s17, s18
	s_add_i32 s14, s14, s17
	s_sub_i32 s15, s19, s14
	s_sub_i32 s15, 0x100, s15
	s_sub_i32 s25, s14, s15
	s_cmp_eq_u32 s25, 0
	s_cbranch_scc1 .Lfn_nodrop
	s_cmpk_le_u32 s25, 3
	s_cbranch_scc1 .Lfn_direct
	v_mov_b32_e32 v92, s21
	v_cvt_f32_u32_e32 v92, v92
	v_rcp_f32_e32 v92, v92
	s_nop 0
	v_mul_f32_e32 v92, 0x4f800000, v92
	v_mul_f32_e32 v92, 0x3f800008, v92
	v_cvt_u32_f32_e32 v92, v92
	v_add_u32_e32 v92, 0x40, v92
	v_cvt_f32_u32_e32 v93, v92
	v_rcp_f32_e32 v93, v93
	s_nop 0
	v_mul_f32_e32 v93, 0x53800000, v93
	v_cvt_u32_f32_e32 v93, v93
	s_nop 0
	v_readfirstlane_b32 s17, v92
	v_readfirstlane_b32 s18, v93
	s_cmpk_le_u32 s17, 0x100
	s_cbranch_scc1 .Lfn_orig
	ds_write_b128 v127, a[206:209]
	s_mov_b64 s[22:23], exec
	v_cmp_eq_u32_e64 s[26:27], s20, v173
	v_subrev_u32_e32 v93, s13, v108
	v_mul_hi_u32 v93, v93, s18
	v_min_u32_e32 v120, 0xff, v93
	v_lshl_add_u32 v93, v120, 2, v121
	s_mov_b64 exec, s[26:27]
	ds_add_u32 v93, v252
	s_mov_b64 exec, s[22:23]
	v_cmp_eq_u32_e64 s[28:29], s20, v174
	v_subrev_u32_e32 v94, s13, v109
	v_mul_hi_u32 v94, v94, s18
	v_min_u32_e32 v122, 0xff, v94
	v_lshl_add_u32 v94, v122, 2, v121
	s_mov_b64 exec, s[28:29]
	ds_add_u32 v94, v252
	s_mov_b64 exec, s[22:23]
	v_cmp_eq_u32_e64 s[30:31], s20, v175
	v_subrev_u32_e32 v95, s13, v110
	v_mul_hi_u32 v95, v95, s18
	v_min_u32_e32 v123, 0xff, v95
	v_lshl_add_u32 v95, v123, 2, v121
	s_mov_b64 exec, s[30:31]
	ds_add_u32 v95, v252
	s_mov_b64 exec, s[22:23]
	v_cmp_eq_u32_e64 s[26:27], s20, v176
	v_subrev_u32_e32 v93, s13, v111
	v_mul_hi_u32 v93, v93, s18
	v_min_u32_e32 v124, 0xff, v93
	v_lshl_add_u32 v93, v124, 2, v121
	s_mov_b64 exec, s[26:27]
	ds_add_u32 v93, v252
	s_mov_b64 exec, s[22:23]
	v_cmp_eq_u32_e64 s[28:29], s20, v177
	v_subrev_u32_e32 v94, s13, v112
	v_mul_hi_u32 v94, v94, s18
	v_min_u32_e32 v126, 0xff, v94
	v_lshl_add_u32 v94, v126, 2, v121
	s_mov_b64 exec, s[28:29]
	ds_add_u32 v94, v252
	s_mov_b64 exec, s[22:23]
	v_cmp_eq_u32_e64 s[30:31], s20, v178
	v_subrev_u32_e32 v95, s13, v113
	v_mul_hi_u32 v95, v95, s18
	v_min_u32_e32 v128, 0xff, v95
	v_lshl_add_u32 v95, v128, 2, v121
	s_mov_b64 exec, s[30:31]
	ds_add_u32 v95, v252
	s_mov_b64 exec, s[22:23]
	v_cmp_eq_u32_e64 s[26:27], s20, v179
	v_subrev_u32_e32 v93, s13, v114
	v_mul_hi_u32 v93, v93, s18
	v_min_u32_e32 v129, 0xff, v93
	v_lshl_add_u32 v93, v129, 2, v121
	s_mov_b64 exec, s[26:27]
	ds_add_u32 v93, v252
	s_mov_b64 exec, s[22:23]
	v_cmp_eq_u32_e64 s[28:29], s20, v180
	v_subrev_u32_e32 v94, s13, v115
	v_mul_hi_u32 v94, v94, s18
	v_min_u32_e32 v130, 0xff, v94
	v_lshl_add_u32 v94, v130, 2, v121
	s_mov_b64 exec, s[28:29]
	ds_add_u32 v94, v252
	s_mov_b64 exec, s[22:23]
	v_cmp_eq_u32_e64 s[30:31], s20, v181
	v_subrev_u32_e32 v95, s13, v116
	v_mul_hi_u32 v95, v95, s18
	v_min_u32_e32 v131, 0xff, v95
	v_lshl_add_u32 v95, v131, 2, v121
	s_mov_b64 exec, s[30:31]
	ds_add_u32 v95, v252
	s_mov_b64 exec, s[22:23]
	v_cmp_eq_u32_e64 s[26:27], s20, v182
	v_subrev_u32_e32 v93, s13, v117
	v_mul_hi_u32 v93, v93, s18
	v_min_u32_e32 v132, 0xff, v93
	v_lshl_add_u32 v93, v132, 2, v121
	s_mov_b64 exec, s[26:27]
	ds_add_u32 v93, v252
	s_mov_b64 exec, s[22:23]
	v_cmp_eq_u32_e64 s[28:29], s20, v183
	v_subrev_u32_e32 v94, s13, v118
	v_mul_hi_u32 v94, v94, s18
	v_min_u32_e32 v134, 0xff, v94
	v_lshl_add_u32 v94, v134, 2, v121
	s_mov_b64 exec, s[28:29]
	ds_add_u32 v94, v252
	s_mov_b64 exec, s[22:23]
	v_cmp_eq_u32_e64 s[30:31], s20, v184
	v_subrev_u32_e32 v95, s13, v119
	v_mul_hi_u32 v95, v95, s18
	v_min_u32_e32 v135, 0xff, v95
	v_lshl_add_u32 v95, v135, 2, v121
	s_mov_b64 exec, s[30:31]
	ds_add_u32 v95, v252
	s_mov_b64 exec, s[22:23]
	ds_read_b128 v[92:95], v127
	s_waitcnt lgkmcnt(0)
	v_add_u32_e32 v136, v92, v93
	v_add3_u32 v136, v136, v94, v95
	v_mov_b32_e32 v137, v136
	s_nop 1
	v_add_u32_dpp v137, v137, v137 row_shr:1 row_mask:0xf bank_mask:0xf bound_ctrl:1
	s_nop 1
	v_add_u32_dpp v137, v137, v137 row_shr:2 row_mask:0xf bank_mask:0xf bound_ctrl:1
	s_nop 1
	v_add_u32_dpp v137, v137, v137 row_shr:4 row_mask:0xf bank_mask:0xf bound_ctrl:1
	s_nop 1
	v_add_u32_dpp v137, v137, v137 row_shr:8 row_mask:0xf bank_mask:0xf bound_ctrl:1
	s_nop 1
	v_add_u32_dpp v137, v137, v137 row_bcast:15 row_mask:0xa bank_mask:0xf
	s_nop 1
	v_add_u32_dpp v137, v137, v137 row_bcast:31 row_mask:0xc bank_mask:0xf
	s_nop 1
	v_readlane_b32 s17, v137, 63
	s_nop 1
	v_sub_u32_e32 v138, s17, v137
	v_add_u32_e32 v140, v138, v95
	v_add_u32_e32 v95, v140, v94
	v_add_u32_e32 v94, v95, v93
	v_add_u32_e32 v93, v94, v92
	v_lshlrev_b32_e32 v92, 2, v190
	v_cmp_le_u32_e64 s[26:27], s15, v94
	v_cmp_le_u32_e64 s[28:29], s15, v95
	v_cmp_le_u32_e64 s[30:31], s15, v140
	v_mov_b32_e32 v137, v92
	v_mov_b32_e32 v136, v93
	v_or_b32_e32 v93, 1, v137
	v_cndmask_b32_e64 v136, v136, v94, s[26:27]
	v_cndmask_b32_e64 v92, v92, v93, s[26:27]
	v_or_b32_e32 v93, 2, v137
	v_cndmask_b32_e64 v136, v136, v95, s[28:29]
	v_cndmask_b32_e64 v92, v92, v93, s[28:29]
	v_or_b32_e32 v93, 3, v137
	v_cndmask_b32_e64 v136, v136, v140, s[30:31]
	v_cndmask_b32_e64 v92, v92, v93, s[30:31]
	v_add_u32_e32 v94, v138, v95
	v_cmp_gt_u32_e64 s[26:27], s15, v138
	v_cmp_le_u32_e64 s[28:29], s15, v136
	s_nop 0
	s_and_b64 s[26:27], s[26:27], s[28:29]
	s_cmp_eq_u64 s[26:27], 0
	s_cbranch_scc1 .Lfn_orig
	s_ff1_i32_b64 s17, s[26:27]
	s_nop 3
	v_readlane_b32 s25, v136, s17
	v_readlane_b32 s14, v92, s17
	s_sub_i32 s25, s25, s15
	s_cmpk_gt_u32 s25, 4
	s_cbranch_scc1 .Lfn_orig
	v_cmp_eq_u32_e64 s[26:27], s20, v173
	v_cmp_gt_u32_e64 s[28:29], s14, v120
	v_cmp_eq_u32_e64 s[30:31], s14, v120
	v_subrev_u32_e32 v93, s13, v108
	v_sub_u32_e32 v94, 0x3fff, v142
	s_and_b64 s[28:29], s[28:29], s[26:27]
	s_and_b64 s[30:31], s[30:31], s[26:27]
	v_lshl_or_b32 v93, v93, 14, v94
	s_nop 1
	v_cndmask_b32_e64 v173, v173, 0, s[28:29]
	v_cndmask_b32_e64 v120, -1, v93, s[30:31]
	v_cmp_eq_u32_e64 s[26:27], s20, v174
	v_cmp_gt_u32_e64 s[28:29], s14, v122
	v_cmp_eq_u32_e64 s[30:31], s14, v122
	v_subrev_u32_e32 v93, s13, v109
	v_sub_u32_e32 v94, 0x3fff, v143
	s_and_b64 s[28:29], s[28:29], s[26:27]
	s_and_b64 s[30:31], s[30:31], s[26:27]
	v_lshl_or_b32 v93, v93, 14, v94
	s_nop 1
	v_cndmask_b32_e64 v174, v174, 0, s[28:29]
	v_cndmask_b32_e64 v122, -1, v93, s[30:31]
	v_cmp_eq_u32_e64 s[26:27], s20, v175
	v_cmp_gt_u32_e64 s[28:29], s14, v123
	v_cmp_eq_u32_e64 s[30:31], s14, v123
	v_subrev_u32_e32 v93, s13, v110
	v_sub_u32_e32 v94, 0x3fff, v144
	s_and_b64 s[28:29], s[28:29], s[26:27]
	s_and_b64 s[30:31], s[30:31], s[26:27]
	v_lshl_or_b32 v93, v93, 14, v94
	s_nop 1
	v_cndmask_b32_e64 v175, v175, 0, s[28:29]
	v_cndmask_b32_e64 v123, -1, v93, s[30:31]
	v_cmp_eq_u32_e64 s[26:27], s20, v176
	v_cmp_gt_u32_e64 s[28:29], s14, v124
	v_cmp_eq_u32_e64 s[30:31], s14, v124
	v_subrev_u32_e32 v93, s13, v111
	v_sub_u32_e32 v94, 0x3fff, v145
	s_and_b64 s[28:29], s[28:29], s[26:27]
	s_and_b64 s[30:31], s[30:31], s[26:27]
	v_lshl_or_b32 v93, v93, 14, v94
	s_nop 1
	v_cndmask_b32_e64 v176, v176, 0, s[28:29]
	v_cndmask_b32_e64 v124, -1, v93, s[30:31]
	v_cmp_eq_u32_e64 s[26:27], s20, v177
	v_cmp_gt_u32_e64 s[28:29], s14, v126
	v_cmp_eq_u32_e64 s[30:31], s14, v126
	v_subrev_u32_e32 v93, s13, v112
	v_sub_u32_e32 v94, 0x3fff, v146
	s_and_b64 s[28:29], s[28:29], s[26:27]
	s_and_b64 s[30:31], s[30:31], s[26:27]
	v_lshl_or_b32 v93, v93, 14, v94
	s_nop 1
	v_cndmask_b32_e64 v177, v177, 0, s[28:29]
	v_cndmask_b32_e64 v126, -1, v93, s[30:31]
	v_cmp_eq_u32_e64 s[26:27], s20, v178
	v_cmp_gt_u32_e64 s[28:29], s14, v128
	v_cmp_eq_u32_e64 s[30:31], s14, v128
	v_subrev_u32_e32 v93, s13, v113
	v_sub_u32_e32 v94, 0x3fff, v148
	s_and_b64 s[28:29], s[28:29], s[26:27]
	s_and_b64 s[30:31], s[30:31], s[26:27]
	v_lshl_or_b32 v93, v93, 14, v94
	s_nop 1
	v_cndmask_b32_e64 v178, v178, 0, s[28:29]
	v_cndmask_b32_e64 v128, -1, v93, s[30:31]
	v_cmp_eq_u32_e64 s[26:27], s20, v179
	v_cmp_gt_u32_e64 s[28:29], s14, v129
	v_cmp_eq_u32_e64 s[30:31], s14, v129
	v_subrev_u32_e32 v93, s13, v114
	v_sub_u32_e32 v94, 0x3fff, v149
	s_and_b64 s[28:29], s[28:29], s[26:27]
	s_and_b64 s[30:31], s[30:31], s[26:27]
	v_lshl_or_b32 v93, v93, 14, v94
	s_nop 1
	v_cndmask_b32_e64 v179, v179, 0, s[28:29]
	v_cndmask_b32_e64 v129, -1, v93, s[30:31]
	v_cmp_eq_u32_e64 s[26:27], s20, v180
	v_cmp_gt_u32_e64 s[28:29], s14, v130
	v_cmp_eq_u32_e64 s[30:31], s14, v130
	v_subrev_u32_e32 v93, s13, v115
	v_sub_u32_e32 v94, 0x3fff, v150
	s_and_b64 s[28:29], s[28:29], s[26:27]
	s_and_b64 s[30:31], s[30:31], s[26:27]
	v_lshl_or_b32 v93, v93, 14, v94
	s_nop 1
	v_cndmask_b32_e64 v180, v180, 0, s[28:29]
	v_cndmask_b32_e64 v130, -1, v93, s[30:31]
	v_cmp_eq_u32_e64 s[26:27], s20, v181
	v_cmp_gt_u32_e64 s[28:29], s14, v131
	v_cmp_eq_u32_e64 s[30:31], s14, v131
	v_subrev_u32_e32 v93, s13, v116
	v_sub_u32_e32 v94, 0x3fff, v152
	s_and_b64 s[28:29], s[28:29], s[26:27]
	s_and_b64 s[30:31], s[30:31], s[26:27]
	v_lshl_or_b32 v93, v93, 14, v94
	s_nop 1
	v_cndmask_b32_e64 v181, v181, 0, s[28:29]
	v_cndmask_b32_e64 v131, -1, v93, s[30:31]
	v_cmp_eq_u32_e64 s[26:27], s20, v182
	v_cmp_gt_u32_e64 s[28:29], s14, v132
	v_cmp_eq_u32_e64 s[30:31], s14, v132
	v_subrev_u32_e32 v93, s13, v117
	v_sub_u32_e32 v94, 0x3fff, v153
	s_and_b64 s[28:29], s[28:29], s[26:27]
	s_and_b64 s[30:31], s[30:31], s[26:27]
	v_lshl_or_b32 v93, v93, 14, v94
	s_nop 1
	v_cndmask_b32_e64 v182, v182, 0, s[28:29]
	v_cndmask_b32_e64 v132, -1, v93, s[30:31]
	v_cmp_eq_u32_e64 s[26:27], s20, v183
	v_cmp_gt_u32_e64 s[28:29], s14, v134
	v_cmp_eq_u32_e64 s[30:31], s14, v134
	v_subrev_u32_e32 v93, s13, v118
	v_sub_u32_e32 v94, 0x3fff, v159
	s_and_b64 s[28:29], s[28:29], s[26:27]
	s_and_b64 s[30:31], s[30:31], s[26:27]
	v_lshl_or_b32 v93, v93, 14, v94
	s_nop 1
	v_cndmask_b32_e64 v183, v183, 0, s[28:29]
	v_cndmask_b32_e64 v134, -1, v93, s[30:31]
	v_cmp_eq_u32_e64 s[26:27], s20, v184
	v_cmp_gt_u32_e64 s[28:29], s14, v135
	v_cmp_eq_u32_e64 s[30:31], s14, v135
	v_subrev_u32_e32 v93, s13, v119
	v_sub_u32_e32 v94, 0x3fff, v160
	s_and_b64 s[28:29], s[28:29], s[26:27]
	s_and_b64 s[30:31], s[30:31], s[26:27]
	v_lshl_or_b32 v93, v93, 14, v94
	s_nop 1
	v_cndmask_b32_e64 v184, v184, 0, s[28:29]
	v_cndmask_b32_e64 v135, -1, v93, s[30:31]
	s_cmp_eq_u32 s25, 0
	s_cbranch_scc1 .Lfn_nodrop
	s_branch .Lfn_drop
